# gn_gate: wave sums by DPP row reductions + readlane instead of six ds_bpermute hops
# speedup vs baseline: 1.0236x; 1.0069x over previous
; __device__ __forceinline__ unsigned pk2(float lo, float hi) { unsigned r; asm("v_cvt_pk_bf16_f32 %0, %1, %2" : "=v"(r) : "v"(lo), "v"(hi)); return r; }
; __device__ __forceinline__ float silu_f(float g) { return g * __builtin_amdgcn_rcpf(1.f + __expf(-g)); }
; __device__ __forceinline__ float wave_sum(float v) {
; #pragma unroll
;     for (int o = 1; o < 64; o <<= 1) v += __shfl_xor(v, o);
;     return v;
; }
; __device__ __forceinline__ void gn_gate(const Params& p) {
;     ...
;     for (int it = gw; it < M_TOK * 2; it += NGW) {
;         const int m = it >> 1, h0 = 4 * (it & 1);
;         u32x4 wf[4], wb[4], wg[4];
; #pragma unroll
;         for (int k = 0; k < 4; ++k) { wf[k] = *((const u32x4*)(OF + (size_t)m * 4096 + (h0 + k) * 512) + lane); wb[k] = *((const u32x4*)(OBp + (size_t)m * 4096 + (h0 + k) * 512) + lane);
;             wg[k] = *((const u32x4*)(proj + (size_t)m * R_IN + 8192 + (h0 + k) * 512) + lane); }
; #pragma unroll
;         for (int k = 0; k < 4; ++k) {
;             float o[8], gv[8];
; #pragma unroll
;             for (int e = 0; e < 4; ++e) { o[2 * e] = bflo(wf[k][e]) + bflo(wb[k][e]); o[2 * e + 1] = bfhi(wf[k][e]) + bfhi(wb[k][e]); gv[2 * e] = bflo(wg[k][e]); gv[2 * e + 1] = bfhi(wg[k][e]); }
;             float s = 0.f;
; #pragma unroll
;             for (int e = 0; e < 8; ++e) s += o[e];
;             const float mean = wave_sum(s) * (1.f / 512); float s2 = 0.f;
; #pragma unroll
;             for (int e = 0; e < 8; ++e) { o[e] -= mean; s2 += o[e] * o[e]; }
;             const float rstd = __builtin_amdgcn_rsqf(wave_sum(s2) * (1.f / 512) + LN_EPS);
;             u32x4 w;
; #pragma unroll
;             for (int e = 0; e < 4; ++e) w[e] = pk2(o[2 * e] * rstd * silu_f(gv[2 * e]), o[2 * e + 1] * rstd * silu_f(gv[2 * e + 1]));
;             *((u32x4*)(proj + (size_t)m * R_IN + 8192 + (h0 + k) * 512) + lane) = w;
.LBB0_197:
	s_ashr_i32 s14, s36, 1
	s_ashr_i32 s15, s14, 31
	s_and_b32 s18, s37, 0x800
	s_lshl_b64 s[16:17], s[14:15], 13
	s_mul_hi_i32 s15, s14, 0x6000
	s_mulk_i32 s14, 0x6000
	s_add_u32 s14, s98, s14
	v_lshl_add_u64 v[0:1], v[24:25], 0, s[16:17]
	v_lshl_add_u64 v[2:3], v[26:27], 0, s[16:17]
	s_addc_u32 s15, s99, s15
	s_lshl_b32 s72, s18, 1
	v_lshl_add_u64 v[0:1], v[0:1], 0, s[72:73]
	v_lshl_add_u64 v[6:7], v[2:3], 0, s[72:73]
	global_load_dwordx4 v[36:39], v[0:1], off
	global_load_dwordx4 v[40:43], v[6:7], off
	v_lshl_add_u64 v[4:5], s[14:15], 0, v[176:177]
	v_lshl_add_u64 v[2:3], v[4:5], 0, s[72:73]
	s_mov_b64 s[14:15], 0x5404000
	v_lshl_add_u64 v[28:29], v[2:3], 0, s[14:15]
	s_mov_b32 s14, 0x5404000
	v_add_co_u32_e32 v60, vcc, s14, v2
	s_add_i32 s36, s36, s33
	s_nop 0
	v_addc_co_u32_e32 v61, vcc, 0, v3, vcc
	global_load_dwordx4 v[44:47], v[60:61], off
	global_load_dwordx4 v[48:51], v[0:1], off offset:1024
	global_load_dwordx4 v[52:55], v[6:7], off offset:1024
	global_load_dwordx4 v[56:59], v[28:29], off offset:1024
	global_load_dwordx4 v[12:15], v[0:1], off offset:2048
	global_load_dwordx4 v[20:23], v[6:7], off offset:2048
	global_load_dwordx4 v[16:19], v[28:29], off offset:2048
	s_nop 0
	global_load_dwordx4 v[0:3], v[0:1], off offset:3072
	s_nop 0
	global_load_dwordx4 v[8:11], v[6:7], off offset:3072
	s_nop 0
	global_load_dwordx4 v[4:7], v[28:29], off offset:3072
	s_add_i32 s37, s37, s19
	s_cmpk_gt_i32 s36, 0x7fff
	s_waitcnt vmcnt(11)
	v_lshlrev_b32_e32 v62, 16, v36
	s_waitcnt vmcnt(10)
	v_lshlrev_b32_e32 v63, 16, v40
	v_and_b32_e32 v40, 0xffff0000, v40
	v_and_b32_e32 v36, 0xffff0000, v36
	v_add_f32_e32 v63, v63, v62
	v_add_f32_e32 v65, v40, v36
	s_waitcnt vmcnt(9)
	v_lshlrev_b32_e32 v40, 16, v44
	v_and_b32_e32 v36, 0xffff0000, v44
	v_lshlrev_b32_e32 v44, 16, v37
	v_lshlrev_b32_e32 v62, 16, v41
	v_and_b32_e32 v41, 0xffff0000, v41
	v_and_b32_e32 v37, 0xffff0000, v37
	v_add_f32_e32 v69, v41, v37
	v_add_f32_e32 v37, 0, v63
	v_add_f32_e32 v67, v62, v44
	v_add_f32_e32 v37, v65, v37
	v_lshlrev_b32_e32 v73, 16, v42
	v_lshlrev_b32_e32 v75, 16, v38
	v_and_b32_e32 v72, 0xffff0000, v42
	v_and_b32_e32 v74, 0xffff0000, v38
	v_add_f32_e32 v37, v67, v37
	v_pk_add_f32 v[72:73], v[74:75], v[72:73]
	v_add_f32_e32 v37, v69, v37
	v_lshlrev_b32_e32 v75, 16, v43
	v_lshlrev_b32_e32 v77, 16, v39
	v_and_b32_e32 v74, 0xffff0000, v43
	v_and_b32_e32 v76, 0xffff0000, v39
	v_add_f32_e32 v37, v73, v37
	v_add_f32_e32 v37, v72, v37
	v_pk_add_f32 v[74:75], v[76:77], v[74:75]
	v_lshlrev_b32_e32 v44, 16, v45
	v_add_f32_e32 v37, v75, v37
	v_add_f32_e32 v37, v74, v37
	s_nop 1
	v_add_f32_dpp v37, v37, v37 quad_perm:[1,0,3,2] row_mask:0xf bank_mask:0xf
	s_nop 1
	v_add_f32_dpp v37, v37, v37 quad_perm:[2,3,0,1] row_mask:0xf bank_mask:0xf
	s_nop 1
	v_add_f32_dpp v37, v37, v37 row_half_mirror row_mask:0xf bank_mask:0xf
	s_nop 1
	v_add_f32_dpp v37, v37, v37 row_mirror row_mask:0xf bank_mask:0xf
	s_nop 1
	v_add_f32_dpp v37, v37, v37 row_bcast:15 row_mask:0xa bank_mask:0xf
	s_nop 1
	v_add_f32_dpp v37, v37, v37 row_bcast:31 row_mask:0xc bank_mask:0xf
	s_nop 1
	v_readlane_b32 s14, v37, 63
	s_nop 1
	v_mov_b32_e32 v37, s14
	v_and_b32_e32 v70, 0xffff0000, v45
	v_lshlrev_b32_e32 v38, 16, v46
	v_and_b32_e32 v42, 0xffff0000, v46
	v_lshlrev_b32_e32 v46, 16, v47
	v_and_b32_e32 v78, 0xffff0000, v47
	v_fmac_f32_e32 v65, 0xbb000000, v37
	v_fmac_f32_e32 v63, 0xbb000000, v37
	v_mul_f32_e32 v39, v65, v65
	v_fmac_f32_e32 v39, v63, v63
	v_fmac_f32_e32 v67, 0xbb000000, v37
	v_fmac_f32_e32 v39, v67, v67
	v_fmac_f32_e32 v69, 0xbb000000, v37
	v_mul_f32_e32 v62, 0x3b000000, v37
	v_fmac_f32_e32 v39, v69, v69
	v_fmamk_f32 v77, v37, 0xbb000000, v73
	v_fmac_f32_e32 v39, v77, v77
	v_fmac_f32_e32 v72, 0xbb000000, v37
	v_pk_add_f32 v[74:75], v[74:75], v[62:63] op_sel_hi:[1,0] neg_lo:[0,1] neg_hi:[0,1]
	v_fmac_f32_e32 v39, v72, v72
	v_pk_mul_f32 v[80:81], v[74:75], v[74:75]
	s_nop 0
	v_add_f32_e32 v37, v81, v39
	v_add_f32_e32 v37, v80, v37
	s_nop 1
	v_add_f32_dpp v37, v37, v37 quad_perm:[1,0,3,2] row_mask:0xf bank_mask:0xf
	s_nop 1
	v_add_f32_dpp v37, v37, v37 quad_perm:[2,3,0,1] row_mask:0xf bank_mask:0xf
	s_nop 1
	v_add_f32_dpp v37, v37, v37 row_half_mirror row_mask:0xf bank_mask:0xf
	s_nop 1
	v_add_f32_dpp v37, v37, v37 row_mirror row_mask:0xf bank_mask:0xf
	s_nop 1
	v_add_f32_dpp v37, v37, v37 row_bcast:15 row_mask:0xa bank_mask:0xf
	s_nop 1
	v_add_f32_dpp v37, v37, v37 row_bcast:31 row_mask:0xc bank_mask:0xf
	s_nop 1
	v_readlane_b32 s14, v37, 63
	s_nop 1
	v_mov_b32_e32 v37, s14
	v_fmamk_f32 v37, v37, 0x3b000000, v82
	v_rsq_f32_e32 v41, v37
	v_mul_f32_e32 v37, 0xbfb8aa3b, v40
	v_exp_f32_e32 v37, v37
	v_mov_b32_e32 v45, v41
	v_mov_b32_e32 v71, v41
	v_add_f32_e32 v37, 1.0, v37
	v_rcp_f32_e32 v62, v37
	v_mul_f32_e32 v37, 0xbfb8aa3b, v36
	v_exp_f32_e32 v37, v37
	v_mov_b32_e32 v43, v41
	v_pk_mul_f32 v[62:63], v[62:63], v[40:41]
	v_mov_b32_e32 v47, v41
	v_add_f32_e32 v37, 1.0, v37
	v_rcp_f32_e32 v64, v37
	v_mov_b32_e32 v37, v41
	v_mul_f32_e32 v39, v62, v63
	v_mov_b32_e32 v79, v41
	v_pk_mul_f32 v[36:37], v[64:65], v[36:37]
	s_waitcnt vmcnt(8)
	v_lshlrev_b32_e32 v63, 16, v51
	v_mul_f32_e32 v36, v36, v37
	v_mul_f32_e32 v37, 0xbfb8aa3b, v44
	v_cvt_pk_bf16_f32 v36, v39, v36
	v_exp_f32_e32 v37, v37
	v_mul_f32_e32 v39, 0xbfb8aa3b, v70
	v_exp_f32_e32 v39, v39
	v_and_b32_e32 v62, 0xffff0000, v51
	v_add_f32_e32 v37, 1.0, v37
	v_rcp_f32_e32 v66, v37
	v_add_f32_e32 v39, 1.0, v39
	v_rcp_f32_e32 v68, v39
	s_waitcnt vmcnt(6)
; __device__ __forceinline__ unsigned pk2(float lo, float hi) { unsigned r; asm("v_cvt_pk_bf16_f32 %0, %1, %2" : "=v"(r) : "v"(lo), "v"(hi)); return r; }
; __device__ __forceinline__ float silu_f(float g) { return g * __builtin_amdgcn_rcpf(1.f + __expf(-g)); }
; __device__ __forceinline__ void gn_gate(const Params& p) {
;     ...
;         for (int k = 0; k < 4; ++k) {
;             float o[8], gv[8];
; #pragma unroll
;             for (int e = 0; e < 4; ++e) { o[2 * e] = bflo(wf[k][e]) + bflo(wb[k][e]); o[2 * e + 1] = bfhi(wf[k][e]) + bfhi(wb[k][e]); gv[2 * e] = bflo(wg[k][e]); gv[2 * e + 1] = bfhi(wg[k][e]); }
;             float s = 0.f;
; #pragma unroll
;             for (int e = 0; e < 8; ++e) s += o[e];
;             const float mean = wave_sum(s) * (1.f / 512); float s2 = 0.f;
; #pragma unroll
;             for (int e = 0; e < 8; ++e) { o[e] -= mean; s2 += o[e] * o[e]; }
;             const float rstd = __builtin_amdgcn_rsqf(wave_sum(s2) * (1.f / 512) + LN_EPS);
;             u32x4 w;
; #pragma unroll
;             for (int e = 0; e < 4; ++e) w[e] = pk2(o[2 * e] * rstd * silu_f(gv[2 * e]), o[2 * e + 1] * rstd * silu_f(gv[2 * e + 1]));
;             *((u32x4*)(proj + (size_t)m * R_IN + 8192 + (h0 + k) * 512) + lane) = w;
	v_and_b32_e32 v64, 0xffff0000, v59
	v_pk_mul_f32 v[44:45], v[66:67], v[44:45]
	s_nop 0
	v_mul_f32_e32 v37, v44, v45
	v_pk_mul_f32 v[44:45], v[68:69], v[70:71]
	s_nop 0
	v_mul_f32_e32 v39, v44, v45
	v_cvt_pk_bf16_f32 v37, v37, v39
	v_mul_f32_e32 v39, 0xbfb8aa3b, v38
	v_exp_f32_e32 v39, v39
	s_nop 0
	v_add_f32_e32 v39, 1.0, v39
	v_rcp_f32_e32 v76, v39
	v_mov_b32_e32 v39, v41
	v_pk_mul_f32 v[38:39], v[76:77], v[38:39]
	s_nop 0
	v_mul_f32_e32 v40, v38, v39
	v_mul_f32_e32 v38, 0xbfb8aa3b, v42
	v_exp_f32_e32 v38, v38
	v_mov_b32_e32 v39, v72
	v_add_f32_e32 v38, 1.0, v38
	v_rcp_f32_e32 v38, v38
	s_nop 0
	v_pk_mul_f32 v[38:39], v[38:39], v[42:43]
	s_nop 0
	v_mul_f32_e32 v38, v38, v39
	v_mul_f32_e32 v39, 0xbfb8aa3b, v46
	v_exp_f32_e32 v39, v39
	v_cvt_pk_bf16_f32 v38, v40, v38
	v_mul_f32_e32 v40, 0xbfb8aa3b, v78
	v_exp_f32_e32 v40, v40
	v_add_f32_e32 v39, 1.0, v39
	v_rcp_f32_e32 v42, v39
	v_mov_b32_e32 v43, v75
	v_add_f32_e32 v40, 1.0, v40
	v_pk_mul_f32 v[42:43], v[42:43], v[46:47]
	s_nop 0
	v_mul_f32_e32 v39, v42, v43
	v_rcp_f32_e32 v42, v40
	v_mov_b32_e32 v43, v74
	v_pk_mul_f32 v[40:41], v[42:43], v[78:79]
	s_nop 0
	v_mul_f32_e32 v40, v40, v41
	v_cvt_pk_bf16_f32 v39, v39, v40
	global_store_dwordx4 v[60:61], v[36:39], off
	v_lshlrev_b32_e32 v40, 16, v56
	v_and_b32_e32 v42, 0xffff0000, v56
	v_lshlrev_b32_e32 v36, 16, v48
	v_lshlrev_b32_e32 v37, 16, v52
	v_add_f32_e32 v37, v37, v36
	v_and_b32_e32 v36, 0xffff0000, v52
	v_and_b32_e32 v38, 0xffff0000, v48
	v_add_f32_e32 v39, v36, v38
	v_lshlrev_b32_e32 v36, 16, v49
	v_lshlrev_b32_e32 v38, 16, v53
	v_add_f32_e32 v45, v38, v36
	v_and_b32_e32 v36, 0xffff0000, v53
	v_and_b32_e32 v38, 0xffff0000, v49
	v_add_f32_e32 v47, v36, v38
	v_add_f32_e32 v36, 0, v37
	v_add_f32_e32 v36, v39, v36
	v_lshlrev_b32_e32 v48, 16, v57
	v_and_b32_e32 v52, 0xffff0000, v57
	v_lshlrev_b32_e32 v57, 16, v54
	v_lshlrev_b32_e32 v61, 16, v50
	v_and_b32_e32 v56, 0xffff0000, v54
	v_and_b32_e32 v60, 0xffff0000, v50
	v_add_f32_e32 v36, v45, v36
	v_pk_add_f32 v[56:57], v[60:61], v[56:57]
	v_add_f32_e32 v36, v47, v36
	v_lshlrev_b32_e32 v61, 16, v55
	v_and_b32_e32 v60, 0xffff0000, v55
	v_add_f32_e32 v36, v57, v36
	v_add_f32_e32 v36, v56, v36
	v_pk_add_f32 v[60:61], v[62:63], v[60:61]
	v_lshlrev_b32_e32 v50, 16, v58
	v_add_f32_e32 v36, v61, v36
	v_add_f32_e32 v36, v60, v36
	s_nop 1
	v_add_f32_dpp v36, v36, v36 quad_perm:[1,0,3,2] row_mask:0xf bank_mask:0xf
	s_nop 1
	v_add_f32_dpp v36, v36, v36 quad_perm:[2,3,0,1] row_mask:0xf bank_mask:0xf
	s_nop 1
	v_add_f32_dpp v36, v36, v36 row_half_mirror row_mask:0xf bank_mask:0xf
	s_nop 1
	v_add_f32_dpp v36, v36, v36 row_mirror row_mask:0xf bank_mask:0xf
	s_nop 1
	v_add_f32_dpp v36, v36, v36 row_bcast:15 row_mask:0xa bank_mask:0xf
	s_nop 1
	v_add_f32_dpp v36, v36, v36 row_bcast:31 row_mask:0xc bank_mask:0xf
	s_nop 1
	v_readlane_b32 s14, v36, 63
	s_nop 1
	v_mov_b32_e32 v38, s14
	v_and_b32_e32 v54, 0xffff0000, v58
	v_lshlrev_b32_e32 v58, 16, v59
	v_fmac_f32_e32 v39, 0xbb000000, v38
	v_fmac_f32_e32 v37, 0xbb000000, v38
	v_mul_f32_e32 v41, v39, v39
	v_fmac_f32_e32 v41, v37, v37
	v_fmac_f32_e32 v45, 0xbb000000, v38
	v_fmac_f32_e32 v41, v45, v45
	v_fmac_f32_e32 v47, 0xbb000000, v38
	v_mul_f32_e32 v36, 0x3b000000, v38
	v_fmac_f32_e32 v41, v47, v47
	v_fmamk_f32 v63, v38, 0xbb000000, v57
	v_fmac_f32_e32 v41, v63, v63
	v_fmac_f32_e32 v56, 0xbb000000, v38
	v_pk_add_f32 v[60:61], v[60:61], v[36:37] op_sel_hi:[1,0] neg_lo:[0,1] neg_hi:[0,1]
	v_fmac_f32_e32 v41, v56, v56
	v_pk_mul_f32 v[66:67], v[60:61], v[60:61]
	s_nop 0
	v_add_f32_e32 v36, v67, v41
	v_add_f32_e32 v36, v66, v36
	s_nop 1
	v_add_f32_dpp v36, v36, v36 quad_perm:[1,0,3,2] row_mask:0xf bank_mask:0xf
	s_nop 1
	v_add_f32_dpp v36, v36, v36 quad_perm:[2,3,0,1] row_mask:0xf bank_mask:0xf
	s_nop 1
	v_add_f32_dpp v36, v36, v36 row_half_mirror row_mask:0xf bank_mask:0xf
	s_nop 1
	v_add_f32_dpp v36, v36, v36 row_mirror row_mask:0xf bank_mask:0xf
	s_nop 1
	v_add_f32_dpp v36, v36, v36 row_bcast:15 row_mask:0xa bank_mask:0xf
	s_nop 1
	v_add_f32_dpp v36, v36, v36 row_bcast:31 row_mask:0xc bank_mask:0xf
	s_nop 1
	v_readlane_b32 s14, v36, 63
	s_nop 1
	v_mov_b32_e32 v36, s14
	v_fmamk_f32 v36, v36, 0x3b000000, v82
	v_rsq_f32_e32 v41, v36
	v_mul_f32_e32 v36, 0xbfb8aa3b, v40
	v_exp_f32_e32 v36, v36
	v_mov_b32_e32 v43, v41
	v_mov_b32_e32 v49, v41
	v_add_f32_e32 v36, 1.0, v36
	v_rcp_f32_e32 v36, v36
	v_mov_b32_e32 v53, v41
	v_mov_b32_e32 v51, v41
	v_mov_b32_e32 v55, v41
	v_pk_mul_f32 v[36:37], v[36:37], v[40:41]
	v_mov_b32_e32 v59, v41
	v_mul_f32_e32 v40, v36, v37
	v_mul_f32_e32 v36, 0xbfb8aa3b, v42
	v_exp_f32_e32 v36, v36
	v_mov_b32_e32 v65, v41
	v_add_f32_e32 v36, 1.0, v36
	v_rcp_f32_e32 v38, v36
	s_nop 0
	v_pk_mul_f32 v[36:37], v[38:39], v[42:43]
	s_nop 0
	v_mul_f32_e32 v36, v36, v37
	v_mul_f32_e32 v37, 0xbfb8aa3b, v48
	v_exp_f32_e32 v37, v37
	v_cvt_pk_bf16_f32 v36, v40, v36
	v_mov_b32_e32 v43, v61
	v_add_f32_e32 v37, 1.0, v37
	v_rcp_f32_e32 v44, v37
	s_nop 0
	v_pk_mul_f32 v[38:39], v[44:45], v[48:49]
	s_nop 0
	v_mul_f32_e32 v37, v38, v39
	v_mul_f32_e32 v38, 0xbfb8aa3b, v52
	v_exp_f32_e32 v38, v38
	s_waitcnt vmcnt(6)
	v_lshlrev_b32_e32 v49, 16, v14
	v_and_b32_e32 v48, 0xffff0000, v14
	s_waitcnt vmcnt(4)
; __device__ __forceinline__ unsigned pk2(float lo, float hi) { unsigned r; asm("v_cvt_pk_bf16_f32 %0, %1, %2" : "=v"(r) : "v"(lo), "v"(hi)); return r; }
; __device__ __forceinline__ float silu_f(float g) { return g * __builtin_amdgcn_rcpf(1.f + __expf(-g)); }
; __device__ __forceinline__ void gn_gate(const Params& p) {
;     ...
;         for (int k = 0; k < 4; ++k) {
;             float o[8], gv[8];
; #pragma unroll
;             for (int e = 0; e < 4; ++e) { o[2 * e] = bflo(wf[k][e]) + bflo(wb[k][e]); o[2 * e + 1] = bfhi(wf[k][e]) + bfhi(wb[k][e]); gv[2 * e] = bflo(wg[k][e]); gv[2 * e + 1] = bfhi(wg[k][e]); }
;             float s = 0.f;
; #pragma unroll
;             for (int e = 0; e < 8; ++e) s += o[e];
;             const float mean = wave_sum(s) * (1.f / 512); float s2 = 0.f;
; #pragma unroll
;             for (int e = 0; e < 8; ++e) { o[e] -= mean; s2 += o[e] * o[e]; }
;             const float rstd = __builtin_amdgcn_rsqf(wave_sum(s2) * (1.f / 512) + LN_EPS);
;             u32x4 w;
; #pragma unroll
;             for (int e = 0; e < 4; ++e) w[e] = pk2(o[2 * e] * rstd * silu_f(gv[2 * e]), o[2 * e + 1] * rstd * silu_f(gv[2 * e + 1]));
;             *((u32x4*)(proj + (size_t)m * R_IN + 8192 + (h0 + k) * 512) + lane) = w;
	v_and_b32_e32 v44, 0xffff0000, v17
	v_add_f32_e32 v38, 1.0, v38
	v_rcp_f32_e32 v46, v38
	v_lshlrev_b32_e32 v14, 16, v18
	v_and_b32_e32 v18, 0xffff0000, v18
	v_pk_mul_f32 v[38:39], v[46:47], v[52:53]
	s_nop 0
	v_mul_f32_e32 v38, v38, v39
	v_cvt_pk_bf16_f32 v37, v37, v38
	v_mul_f32_e32 v38, 0xbfb8aa3b, v50
	v_exp_f32_e32 v38, v38
	v_lshlrev_b32_e32 v47, 16, v22
	v_and_b32_e32 v46, 0xffff0000, v22
	v_pk_add_f32 v[46:47], v[48:49], v[46:47]
	v_add_f32_e32 v38, 1.0, v38
	v_rcp_f32_e32 v62, v38
	v_lshlrev_b32_e32 v49, 16, v23
	v_and_b32_e32 v48, 0xffff0000, v23
	v_lshlrev_b32_e32 v22, 16, v19
	v_pk_mul_f32 v[38:39], v[62:63], v[50:51]
	v_lshlrev_b32_e32 v51, 16, v15
	v_mul_f32_e32 v40, v38, v39
	v_mul_f32_e32 v38, 0xbfb8aa3b, v54
	v_exp_f32_e32 v38, v38
	v_mov_b32_e32 v39, v56
	v_and_b32_e32 v50, 0xffff0000, v15
	v_pk_add_f32 v[48:49], v[50:51], v[48:49]
	v_add_f32_e32 v38, 1.0, v38
	v_rcp_f32_e32 v38, v38
	v_and_b32_e32 v52, 0xffff0000, v19
	v_pk_mul_f32 v[38:39], v[38:39], v[54:55]
	s_nop 0
	v_mul_f32_e32 v38, v38, v39
	v_mul_f32_e32 v39, 0xbfb8aa3b, v58
	v_exp_f32_e32 v39, v39
	v_cvt_pk_bf16_f32 v38, v40, v38
	v_mul_f32_e32 v40, 0xbfb8aa3b, v64
	v_exp_f32_e32 v40, v40
	v_add_f32_e32 v39, 1.0, v39
	v_rcp_f32_e32 v42, v39
	v_add_f32_e32 v40, 1.0, v40
	v_pk_mul_f32 v[42:43], v[42:43], v[58:59]
	s_nop 0
	v_mul_f32_e32 v39, v42, v43
	v_rcp_f32_e32 v42, v40
	v_mov_b32_e32 v43, v60
	v_pk_mul_f32 v[40:41], v[42:43], v[64:65]
	s_nop 0
	v_mul_f32_e32 v40, v40, v41
	v_cvt_pk_bf16_f32 v39, v39, v40
	global_store_dwordx4 v[28:29], v[36:39], off offset:1024
	s_nop 1
	v_lshlrev_b32_e32 v36, 16, v12
	v_lshlrev_b32_e32 v37, 16, v20
	v_and_b32_e32 v20, 0xffff0000, v20
	v_and_b32_e32 v12, 0xffff0000, v12
	v_add_f32_e32 v37, v37, v36
	v_add_f32_e32 v39, v20, v12
	v_lshlrev_b32_e32 v20, 16, v16
	v_and_b32_e32 v12, 0xffff0000, v16
	v_lshlrev_b32_e32 v16, 16, v13
	v_lshlrev_b32_e32 v36, 16, v21
	v_add_f32_e32 v41, v36, v16
	v_and_b32_e32 v16, 0xffff0000, v21
	v_and_b32_e32 v13, 0xffff0000, v13
	v_add_f32_e32 v43, v16, v13
	v_add_f32_e32 v13, 0, v37
	v_add_f32_e32 v13, v39, v13
	v_add_f32_e32 v13, v41, v13
	v_add_f32_e32 v13, v43, v13
	v_add_f32_e32 v13, v47, v13
	v_add_f32_e32 v13, v46, v13
	v_add_f32_e32 v13, v49, v13
	v_add_f32_e32 v13, v48, v13
	s_nop 1
	v_add_f32_dpp v13, v13, v13 quad_perm:[1,0,3,2] row_mask:0xf bank_mask:0xf
	s_nop 1
	v_add_f32_dpp v13, v13, v13 quad_perm:[2,3,0,1] row_mask:0xf bank_mask:0xf
	s_nop 1
	v_add_f32_dpp v13, v13, v13 row_half_mirror row_mask:0xf bank_mask:0xf
	s_nop 1
	v_add_f32_dpp v13, v13, v13 row_mirror row_mask:0xf bank_mask:0xf
	s_nop 1
	v_add_f32_dpp v13, v13, v13 row_bcast:15 row_mask:0xa bank_mask:0xf
	s_nop 1
	v_add_f32_dpp v13, v13, v13 row_bcast:31 row_mask:0xc bank_mask:0xf
	s_nop 1
	v_readlane_b32 s14, v13, 63
	s_nop 1
	v_mov_b32_e32 v13, s14
	v_lshlrev_b32_e32 v16, 16, v17
	v_fmac_f32_e32 v39, 0xbb000000, v13
	v_fmac_f32_e32 v37, 0xbb000000, v13
	v_mul_f32_e32 v15, v39, v39
	v_fmac_f32_e32 v15, v37, v37
	v_fmac_f32_e32 v41, 0xbb000000, v13
	v_fmac_f32_e32 v15, v41, v41
	v_fmac_f32_e32 v43, 0xbb000000, v13
	v_mul_f32_e32 v36, 0x3b000000, v13
	v_fmac_f32_e32 v15, v43, v43
	v_fmamk_f32 v51, v13, 0xbb000000, v47
	v_fmac_f32_e32 v15, v51, v51
	v_fmac_f32_e32 v46, 0xbb000000, v13
	v_pk_add_f32 v[48:49], v[48:49], v[36:37] op_sel_hi:[1,0] neg_lo:[0,1] neg_hi:[0,1]
	v_fmac_f32_e32 v15, v46, v46
	v_pk_mul_f32 v[54:55], v[48:49], v[48:49]
	s_nop 0
	v_add_f32_e32 v13, v55, v15
	v_add_f32_e32 v13, v54, v13
	s_nop 1
	v_add_f32_dpp v13, v13, v13 quad_perm:[1,0,3,2] row_mask:0xf bank_mask:0xf
	s_nop 1
	v_add_f32_dpp v13, v13, v13 quad_perm:[2,3,0,1] row_mask:0xf bank_mask:0xf
	s_nop 1
	v_add_f32_dpp v13, v13, v13 row_half_mirror row_mask:0xf bank_mask:0xf
	s_nop 1
	v_add_f32_dpp v13, v13, v13 row_mirror row_mask:0xf bank_mask:0xf
	s_nop 1
	v_add_f32_dpp v13, v13, v13 row_bcast:15 row_mask:0xa bank_mask:0xf
	s_nop 1
	v_add_f32_dpp v13, v13, v13 row_bcast:31 row_mask:0xc bank_mask:0xf
	s_nop 1
	v_readlane_b32 s14, v13, 63
	s_nop 1
	v_mov_b32_e32 v13, s14
	v_fmamk_f32 v13, v13, 0x3b000000, v82
	v_rsq_f32_e32 v21, v13
	v_mul_f32_e32 v13, 0xbfb8aa3b, v20
	v_exp_f32_e32 v13, v13
	v_mov_b32_e32 v17, v21
	v_mov_b32_e32 v45, v21
	v_add_f32_e32 v13, 1.0, v13
	v_rcp_f32_e32 v36, v13
	v_mul_f32_e32 v13, 0xbfb8aa3b, v12
	v_exp_f32_e32 v13, v13
	v_mov_b32_e32 v19, v21
	v_pk_mul_f32 v[36:37], v[36:37], v[20:21]
	v_mov_b32_e32 v23, v21
	v_add_f32_e32 v13, 1.0, v13
	v_rcp_f32_e32 v38, v13
	v_mov_b32_e32 v13, v21
	v_mul_f32_e32 v15, v36, v37
	v_mov_b32_e32 v53, v21
	v_pk_mul_f32 v[12:13], v[38:39], v[12:13]
	s_waitcnt vmcnt(4)
	v_lshlrev_b32_e32 v37, 16, v2
	v_mul_f32_e32 v12, v12, v13
	v_mul_f32_e32 v13, 0xbfb8aa3b, v16
	v_cvt_pk_bf16_f32 v12, v15, v12
	v_exp_f32_e32 v13, v13
	v_mul_f32_e32 v15, 0xbfb8aa3b, v44
	v_exp_f32_e32 v15, v15
	v_and_b32_e32 v36, 0xffff0000, v2
	v_add_f32_e32 v13, 1.0, v13
	v_rcp_f32_e32 v40, v13
	v_add_f32_e32 v15, 1.0, v15
	v_rcp_f32_e32 v42, v15
	v_lshlrev_b32_e32 v39, 16, v3
	v_pk_mul_f32 v[16:17], v[40:41], v[16:17]
	v_and_b32_e32 v38, 0xffff0000, v3
	v_mul_f32_e32 v13, v16, v17
	v_pk_mul_f32 v[16:17], v[42:43], v[44:45]
	s_waitcnt vmcnt(2)
; __device__ __forceinline__ unsigned pk2(float lo, float hi) { unsigned r; asm("v_cvt_pk_bf16_f32 %0, %1, %2" : "=v"(r) : "v"(lo), "v"(hi)); return r; }
; __device__ __forceinline__ float silu_f(float g) { return g * __builtin_amdgcn_rcpf(1.f + __expf(-g)); }
; __device__ __forceinline__ float wave_sum(float v) {
; #pragma unroll
;     for (int o = 1; o < 64; o <<= 1) v += __shfl_xor(v, o);
;     return v;
; __device__ __forceinline__ void gn_gate(const Params& p) {
;     ...
;         for (int k = 0; k < 4; ++k) {
;             float o[8], gv[8];
; #pragma unroll
;             for (int e = 0; e < 4; ++e) { o[2 * e] = bflo(wf[k][e]) + bflo(wb[k][e]); o[2 * e + 1] = bfhi(wf[k][e]) + bfhi(wb[k][e]); gv[2 * e] = bflo(wg[k][e]); gv[2 * e + 1] = bfhi(wg[k][e]); }
;             float s = 0.f;
; #pragma unroll
;             for (int e = 0; e < 8; ++e) s += o[e];
;             const float mean = wave_sum(s) * (1.f / 512); float s2 = 0.f;
; #pragma unroll
;             for (int e = 0; e < 8; ++e) { o[e] -= mean; s2 += o[e] * o[e]; }
;             const float rstd = __builtin_amdgcn_rsqf(wave_sum(s2) * (1.f / 512) + LN_EPS);
;             u32x4 w;
; #pragma unroll
;             for (int e = 0; e < 4; ++e) w[e] = pk2(o[2 * e] * rstd * silu_f(gv[2 * e]), o[2 * e + 1] * rstd * silu_f(gv[2 * e + 1]));
;             *((u32x4*)(proj + (size_t)m * R_IN + 8192 + (h0 + k) * 512) + lane) = w;
	v_and_b32_e32 v20, 0xffff0000, v5
	v_mul_f32_e32 v15, v16, v17
	v_cvt_pk_bf16_f32 v13, v13, v15
	v_mul_f32_e32 v15, 0xbfb8aa3b, v14
	v_exp_f32_e32 v15, v15
	v_mov_b32_e32 v17, v49
	v_lshlrev_b32_e32 v2, 16, v6
	v_and_b32_e32 v6, 0xffff0000, v6
	v_add_f32_e32 v15, 1.0, v15
	v_rcp_f32_e32 v50, v15
	v_mov_b32_e32 v15, v21
	v_and_b32_e32 v40, 0xffff0000, v7
	v_pk_mul_f32 v[14:15], v[50:51], v[14:15]
	s_nop 0
	v_mul_f32_e32 v16, v14, v15
	v_mul_f32_e32 v14, 0xbfb8aa3b, v18
	v_exp_f32_e32 v14, v14
	v_mov_b32_e32 v15, v46
	v_add_f32_e32 v14, 1.0, v14
	v_rcp_f32_e32 v14, v14
	s_nop 0
	v_pk_mul_f32 v[14:15], v[14:15], v[18:19]
	s_nop 0
	v_mul_f32_e32 v14, v14, v15
	v_mul_f32_e32 v15, 0xbfb8aa3b, v22
	v_exp_f32_e32 v15, v15
	v_cvt_pk_bf16_f32 v14, v16, v14
	s_nop 0
	v_add_f32_e32 v15, 1.0, v15
	v_rcp_f32_e32 v16, v15
	s_nop 0
	v_pk_mul_f32 v[16:17], v[16:17], v[22:23]
	s_nop 0
	v_mul_f32_e32 v15, v16, v17
	v_mul_f32_e32 v16, 0xbfb8aa3b, v52
	v_exp_f32_e32 v16, v16
	v_mov_b32_e32 v17, v48
	v_lshlrev_b32_e32 v23, 16, v10
	v_and_b32_e32 v22, 0xffff0000, v10
	v_add_f32_e32 v16, 1.0, v16
	v_rcp_f32_e32 v16, v16
	v_pk_add_f32 v[22:23], v[36:37], v[22:23]
	v_lshlrev_b32_e32 v37, 16, v11
	v_and_b32_e32 v36, 0xffff0000, v11
	v_pk_mul_f32 v[16:17], v[16:17], v[52:53]
	v_pk_add_f32 v[36:37], v[38:39], v[36:37]
	v_mul_f32_e32 v16, v16, v17
	v_cvt_pk_bf16_f32 v15, v15, v16
	global_store_dwordx4 v[28:29], v[12:15], off offset:2048
	v_lshlrev_b32_e32 v10, 16, v7
	s_nop 0
	v_lshlrev_b32_e32 v12, 16, v0
	v_lshlrev_b32_e32 v13, 16, v8
	v_and_b32_e32 v8, 0xffff0000, v8
	v_and_b32_e32 v0, 0xffff0000, v0
	v_add_f32_e32 v13, v13, v12
	v_add_f32_e32 v15, v8, v0
	v_lshlrev_b32_e32 v8, 16, v4
	v_and_b32_e32 v0, 0xffff0000, v4
	v_lshlrev_b32_e32 v4, 16, v1
	v_lshlrev_b32_e32 v12, 16, v9
	v_add_f32_e32 v17, v12, v4
	v_and_b32_e32 v4, 0xffff0000, v9
	v_and_b32_e32 v1, 0xffff0000, v1
	v_add_f32_e32 v19, v4, v1
	v_add_f32_e32 v1, 0, v13
	v_add_f32_e32 v1, v15, v1
	v_add_f32_e32 v1, v17, v1
	v_add_f32_e32 v1, v19, v1
	v_add_f32_e32 v1, v23, v1
	v_add_f32_e32 v1, v22, v1
	v_add_f32_e32 v1, v37, v1
	v_add_f32_e32 v1, v36, v1
	s_nop 1
	v_add_f32_dpp v1, v1, v1 quad_perm:[1,0,3,2] row_mask:0xf bank_mask:0xf
	s_nop 1
	v_add_f32_dpp v1, v1, v1 quad_perm:[2,3,0,1] row_mask:0xf bank_mask:0xf
	s_nop 1
	v_add_f32_dpp v1, v1, v1 row_half_mirror row_mask:0xf bank_mask:0xf
	s_nop 1
	v_add_f32_dpp v1, v1, v1 row_mirror row_mask:0xf bank_mask:0xf
	s_nop 1
	v_add_f32_dpp v1, v1, v1 row_bcast:15 row_mask:0xa bank_mask:0xf
	s_nop 1
	v_add_f32_dpp v1, v1, v1 row_bcast:31 row_mask:0xc bank_mask:0xf
	s_nop 1
	v_readlane_b32 s14, v1, 63
	s_nop 1
	v_mov_b32_e32 v1, s14
	v_lshlrev_b32_e32 v4, 16, v5
	v_fmac_f32_e32 v15, 0xbb000000, v1
	v_fmac_f32_e32 v13, 0xbb000000, v1
	v_mul_f32_e32 v3, v15, v15
	v_fmac_f32_e32 v3, v13, v13
	v_fmac_f32_e32 v17, 0xbb000000, v1
	v_fmac_f32_e32 v3, v17, v17
	v_fmac_f32_e32 v19, 0xbb000000, v1
	v_mul_f32_e32 v12, 0x3b000000, v1
	v_fmac_f32_e32 v3, v19, v19
	v_fmamk_f32 v39, v1, 0xbb000000, v23
	v_fmac_f32_e32 v3, v39, v39
	v_fmac_f32_e32 v22, 0xbb000000, v1
	v_pk_add_f32 v[36:37], v[36:37], v[12:13] op_sel_hi:[1,0] neg_lo:[0,1] neg_hi:[0,1]
	v_fmac_f32_e32 v3, v22, v22
	v_pk_mul_f32 v[42:43], v[36:37], v[36:37]
	s_nop 0
	v_add_f32_e32 v1, v43, v3
	v_add_f32_e32 v1, v42, v1
	s_nop 1
	v_add_f32_dpp v1, v1, v1 quad_perm:[1,0,3,2] row_mask:0xf bank_mask:0xf
	s_nop 1
	v_add_f32_dpp v1, v1, v1 quad_perm:[2,3,0,1] row_mask:0xf bank_mask:0xf
	s_nop 1
	v_add_f32_dpp v1, v1, v1 row_half_mirror row_mask:0xf bank_mask:0xf
	s_nop 1
	v_add_f32_dpp v1, v1, v1 row_mirror row_mask:0xf bank_mask:0xf
	s_nop 1
	v_add_f32_dpp v1, v1, v1 row_bcast:15 row_mask:0xa bank_mask:0xf
	s_nop 1
	v_add_f32_dpp v1, v1, v1 row_bcast:31 row_mask:0xc bank_mask:0xf
	s_nop 1
	v_readlane_b32 s14, v1, 63
	s_nop 1
	v_mov_b32_e32 v1, s14
	v_fmamk_f32 v1, v1, 0x3b000000, v82
	v_rsq_f32_e32 v9, v1
	v_mul_f32_e32 v1, 0xbfb8aa3b, v8
	v_exp_f32_e32 v1, v1
	v_mov_b32_e32 v5, v9
	v_mov_b32_e32 v21, v9
	v_add_f32_e32 v1, 1.0, v1
	v_rcp_f32_e32 v12, v1
	v_mul_f32_e32 v1, 0xbfb8aa3b, v0
	v_exp_f32_e32 v1, v1
	v_mov_b32_e32 v7, v9
	v_pk_mul_f32 v[12:13], v[12:13], v[8:9]
	v_mov_b32_e32 v11, v9
	v_add_f32_e32 v1, 1.0, v1
	v_rcp_f32_e32 v14, v1
	v_mov_b32_e32 v1, v9
	v_mul_f32_e32 v3, v12, v13
	v_mov_b32_e32 v41, v9
	v_pk_mul_f32 v[0:1], v[14:15], v[0:1]
	s_nop 0
	v_mul_f32_e32 v0, v0, v1
	v_mul_f32_e32 v1, 0xbfb8aa3b, v4
	v_cvt_pk_bf16_f32 v0, v3, v0
	v_exp_f32_e32 v1, v1
	v_mul_f32_e32 v3, 0xbfb8aa3b, v20
	v_exp_f32_e32 v3, v3
	v_add_f32_e32 v1, 1.0, v1
	v_rcp_f32_e32 v16, v1
	v_add_f32_e32 v3, 1.0, v3
	v_rcp_f32_e32 v18, v3
	v_pk_mul_f32 v[4:5], v[16:17], v[4:5]
	s_nop 0
	v_mul_f32_e32 v1, v4, v5
	v_pk_mul_f32 v[4:5], v[18:19], v[20:21]
	s_nop 0
	v_mul_f32_e32 v3, v4, v5
	v_cvt_pk_bf16_f32 v1, v1, v3
	v_mul_f32_e32 v3, 0xbfb8aa3b, v2
	v_exp_f32_e32 v3, v3
	v_mov_b32_e32 v5, v37
	v_add_f32_e32 v3, 1.0, v3
	v_rcp_f32_e32 v38, v3
	v_mov_b32_e32 v3, v9
	v_pk_mul_f32 v[2:3], v[38:39], v[2:3]
	s_nop 0
	v_mul_f32_e32 v4, v2, v3
	v_mul_f32_e32 v2, 0xbfb8aa3b, v6
	v_exp_f32_e32 v2, v2
	v_mov_b32_e32 v3, v22
	v_add_f32_e32 v2, 1.0, v2
	v_rcp_f32_e32 v2, v2
	s_nop 0
	v_pk_mul_f32 v[2:3], v[2:3], v[6:7]
	s_nop 0
	v_mul_f32_e32 v2, v2, v3
	v_mul_f32_e32 v3, 0xbfb8aa3b, v10
	v_exp_f32_e32 v3, v3
	v_cvt_pk_bf16_f32 v2, v4, v2
	s_nop 0
	v_add_f32_e32 v3, 1.0, v3
	v_rcp_f32_e32 v4, v3
	s_nop 0
	v_pk_mul_f32 v[4:5], v[4:5], v[10:11]
	s_nop 0
	v_mul_f32_e32 v3, v4, v5
	v_mul_f32_e32 v4, 0xbfb8aa3b, v40
	v_exp_f32_e32 v4, v4
	v_mov_b32_e32 v5, v36
	v_add_f32_e32 v4, 1.0, v4
	v_rcp_f32_e32 v4, v4
	s_nop 0
	v_pk_mul_f32 v[4:5], v[4:5], v[40:41]
	s_nop 0
	v_mul_f32_e32 v4, v4, v5
	v_cvt_pk_bf16_f32 v3, v3, v4
	global_store_dwordx4 v[28:29], v[0:3], off offset:3072
	s_cbranch_scc0 .LBB0_197
